# v44 plus weight-conversion gain loads left in flight during the drain (wait and multiply moved to the LDS commit)
# speedup vs baseline: 1.0060x; 1.0060x over previous
; #define LAS __attribute__((address_space(3)))
; template <bool NT = false>
; __device__ __forceinline__ void wconv_load(const WItem& t, f32x4 (&v)[8]) {
;     const int tid = threadIdx.x;
; #pragma unroll
;     for (int i = 0; i < 8; ++i) {
;         const int idx = tid + i * 512, kk = idx >> 6, c4 = (idx & 63) * 4;
;         v[i] = (f32x4){0.f, 0.f, 0.f, 0.f};
;         if (t.n0 + c4 + 3 < t.ncols) { const f32x4* sp = (const f32x4*)(t.src + (size_t)(t.k0 + kk) * t.ld + t.n0 + c4); v[i] = NT ? __builtin_nontemporal_load(sp) : *sp; }
;         if (t.gk) v[i] = v[i] * t.gk[t.k0 + kk];
;     }
; }
; __global__ void __launch_bounds__(512, 2) mk_fwd(Args a) {
;     ...
;             { LAS float* tile = (LAS float*)lds; f32x4 v[8]; int it = bid;
;               if (it < 3364) wconv_load(p0_witem(it, a.in, ws), v);
.LBB0_27:
	v_add_u32_e32 v0, s34, v52
	v_cmp_gt_i32_e64 s[4:5], s33, v0
	v_add_u32_e32 v98, s68, v168
	v_lshlrev_b32_e32 v112, 2, v41
	v_mov_b32_e32 v113, 0
	v_mov_b32_e32 v169, 0
	v_mov_b32_e32 v0, 0
	v_mov_b32_e32 v1, 0
	v_mov_b32_e32 v2, 0
	v_mov_b32_e32 v3, 0
	v_mov_b32_e32 v4, 0
	v_mov_b32_e32 v5, 0
	v_mov_b32_e32 v6, 0
	v_mov_b32_e32 v7, 0
	v_mov_b32_e32 v8, 0
	v_mov_b32_e32 v9, 0
	v_mov_b32_e32 v10, 0
	v_mov_b32_e32 v11, 0
	v_mov_b32_e32 v12, 0
	v_mov_b32_e32 v13, 0
	v_mov_b32_e32 v14, 0
	v_mov_b32_e32 v15, 0
	v_mov_b32_e32 v16, 0
	v_mov_b32_e32 v17, 0
	v_mov_b32_e32 v18, 0
	v_mov_b32_e32 v19, 0
	v_mov_b32_e32 v20, 0
	v_mov_b32_e32 v21, 0
	v_mov_b32_e32 v22, 0
	v_mov_b32_e32 v23, 0
	v_mov_b32_e32 v24, 0
	v_mov_b32_e32 v25, 0
	v_mov_b32_e32 v26, 0
	v_mov_b32_e32 v27, 0
	v_mov_b32_e32 v28, 0
	v_mov_b32_e32 v29, 0
	v_mov_b32_e32 v30, 0
	v_mov_b32_e32 v31, 0
	v_mov_b32_e32 v114, 0
	v_lshlrev_b32_e64 v100, 5, s33
	v_mov_b32_e32 v101, 0
	v_mov_b32_e32 v99, 0
	s_and_saveexec_b64 s[6:7], s[4:5]
	s_cbranch_execz .Lw0p_ld_done
	v_mad_u64_u32 v[96:97], s[8:9], v98, s33, 0
	v_lshl_add_u64 v[96:97], v[96:97], 2, s[30:31]
	s_ashr_i32 s35, s34, 31
	v_lshl_add_u64 v[96:97], s[34:35], 2, v[96:97]
	v_lshl_add_u64 v[96:97], v[96:97], 0, v[112:113]
	global_load_dwordx4 v[0:3], v[96:97], off
	v_lshl_add_u64 v[96:97], v[96:97], 0, v[100:101]
	global_load_dwordx4 v[4:7], v[96:97], off
	v_lshl_add_u64 v[96:97], v[96:97], 0, v[100:101]
	global_load_dwordx4 v[8:11], v[96:97], off
	v_lshl_add_u64 v[96:97], v[96:97], 0, v[100:101]
	global_load_dwordx4 v[12:15], v[96:97], off
	v_lshl_add_u64 v[96:97], v[96:97], 0, v[100:101]
	global_load_dwordx4 v[16:19], v[96:97], off
	v_lshl_add_u64 v[96:97], v[96:97], 0, v[100:101]
	global_load_dwordx4 v[20:23], v[96:97], off
	v_lshl_add_u64 v[96:97], v[96:97], 0, v[100:101]
	global_load_dwordx4 v[24:27], v[96:97], off
	v_lshl_add_u64 v[96:97], v[96:97], 0, v[100:101]
	global_load_dwordx4 v[28:31], v[96:97], off

; #define LAS __attribute__((address_space(3)))
; template <bool NT = false>
; __device__ __forceinline__ void wconv_load(const WItem& t, f32x4 (&v)[8]) {
;     ...
;         if (t.gk) v[i] = v[i] * t.gk[t.k0 + kk];
;     }
; }
; __device__ __forceinline__ void wconv_commit(const f32x4 (&v)[8], LAS float* tile) {
;     const int tid = threadIdx.x;
; #pragma unroll
;     for (int i = 0; i < 8; ++i) {
;         const int idx = tid + i * 512, kk = idx >> 6, c4 = (idx & 63) * 4;
;         tile[kk * 257 + c4 + 0] = v[i][0]; tile[kk * 257 + c4 + 1] = v[i][1]; tile[kk * 257 + c4 + 2] = v[i][2]; tile[kk * 257 + c4 + 3] = v[i][3];
.LBB0_63:
	s_waitcnt vmcnt(0)
	v_cmp_ne_u32_e32 vcc, 0, v114
	s_cbranch_vccz .Lw0_nomul
	v_mul_f32_e32 v0, v104, v0
	v_mul_f32_e32 v1, v104, v1
	v_mul_f32_e32 v2, v104, v2
	v_mul_f32_e32 v3, v104, v3
	v_mul_f32_e32 v4, v105, v4
	v_mul_f32_e32 v5, v105, v5
	v_mul_f32_e32 v6, v105, v6
	v_mul_f32_e32 v7, v105, v7
	v_mul_f32_e32 v8, v106, v8
	v_mul_f32_e32 v9, v106, v9
	v_mul_f32_e32 v10, v106, v10
	v_mul_f32_e32 v11, v106, v11
	v_mul_f32_e32 v12, v107, v12
	v_mul_f32_e32 v13, v107, v13
	v_mul_f32_e32 v14, v107, v14
	v_mul_f32_e32 v15, v107, v15
	v_mul_f32_e32 v16, v108, v16
	v_mul_f32_e32 v17, v108, v17
	v_mul_f32_e32 v18, v108, v18
	v_mul_f32_e32 v19, v108, v19
	v_mul_f32_e32 v20, v109, v20
	v_mul_f32_e32 v21, v109, v21
	v_mul_f32_e32 v22, v109, v22
	v_mul_f32_e32 v23, v109, v23
	v_mul_f32_e32 v24, v110, v24
	v_mul_f32_e32 v25, v110, v25
	v_mul_f32_e32 v26, v110, v26
	v_mul_f32_e32 v27, v110, v27
	v_mul_f32_e32 v28, v111, v28
	v_mul_f32_e32 v29, v111, v29
	v_mul_f32_e32 v30, v111, v30
	v_mul_f32_e32 v31, v111, v31
	v_mov_b32_e32 v114, 0

; template <bool NT = false>
; __device__ __forceinline__ void wconv_load(const WItem& t, f32x4 (&v)[8]) {
;     const int tid = threadIdx.x;
; #pragma unroll
;     for (int i = 0; i < 8; ++i) {
;         const int idx = tid + i * 512, kk = idx >> 6, c4 = (idx & 63) * 4;
;         v[i] = (f32x4){0.f, 0.f, 0.f, 0.f};
;         if (t.n0 + c4 + 3 < t.ncols) { const f32x4* sp = (const f32x4*)(t.src + (size_t)(t.k0 + kk) * t.ld + t.n0 + c4); v[i] = NT ? __builtin_nontemporal_load(sp) : *sp; }
;         if (t.gk) v[i] = v[i] * t.gk[t.k0 + kk];
;     }
; }
; __global__ void __launch_bounds__(512, 2) mk_fwd(Args a) {
;     ...
;               while (it < 3364) { wconv_commit(v, tile); __syncthreads(); const int nx = it + G; if (nx < 3364) wconv_load(p0_witem(nx, a.in, ws), v);
.LBB0_92:
	v_add_u32_e32 v0, s84, v52
	v_cmp_gt_i32_e64 s[4:5], s39, v0
	v_add_u32_e32 v98, s82, v168
	v_lshlrev_b32_e32 v38, 2, v41
	v_mov_b32_e32 v0, 0
	v_mov_b32_e32 v1, 0
	v_mov_b32_e32 v2, 0
	v_mov_b32_e32 v3, 0
	v_mov_b32_e32 v4, 0
	v_mov_b32_e32 v5, 0
	v_mov_b32_e32 v6, 0
	v_mov_b32_e32 v7, 0
	v_mov_b32_e32 v8, 0
	v_mov_b32_e32 v9, 0
	v_mov_b32_e32 v10, 0
	v_mov_b32_e32 v11, 0
	v_mov_b32_e32 v12, 0
	v_mov_b32_e32 v13, 0
	v_mov_b32_e32 v14, 0
	v_mov_b32_e32 v15, 0
	v_mov_b32_e32 v16, 0
	v_mov_b32_e32 v17, 0
	v_mov_b32_e32 v18, 0
	v_mov_b32_e32 v19, 0
	v_mov_b32_e32 v20, 0
	v_mov_b32_e32 v21, 0
	v_mov_b32_e32 v22, 0
	v_mov_b32_e32 v23, 0
	v_mov_b32_e32 v24, 0
	v_mov_b32_e32 v25, 0
	v_mov_b32_e32 v26, 0
	v_mov_b32_e32 v27, 0
	v_mov_b32_e32 v28, 0
	v_mov_b32_e32 v29, 0
	v_mov_b32_e32 v30, 0
	v_mov_b32_e32 v31, 0
	v_mov_b32_e32 v114, 0
	v_lshlrev_b32_e64 v100, 5, s39
	v_mov_b32_e32 v101, 0
	v_mov_b32_e32 v99, 0
	s_and_saveexec_b64 s[6:7], s[4:5]
	s_cbranch_execz .Lw0_ld_done
	v_mad_u64_u32 v[96:97], s[8:9], v98, s39, 0
	v_lshl_add_u64 v[96:97], v[96:97], 2, s[80:81]
	s_ashr_i32 s85, s84, 31
	v_lshl_add_u64 v[96:97], s[84:85], 2, v[96:97]
	v_lshl_add_u64 v[96:97], v[96:97], 0, v[38:39]
	global_load_dwordx4 v[0:3], v[96:97], off
	v_lshl_add_u64 v[96:97], v[96:97], 0, v[100:101]
	global_load_dwordx4 v[4:7], v[96:97], off
	v_lshl_add_u64 v[96:97], v[96:97], 0, v[100:101]
	global_load_dwordx4 v[8:11], v[96:97], off
	v_lshl_add_u64 v[96:97], v[96:97], 0, v[100:101]
	global_load_dwordx4 v[12:15], v[96:97], off
	v_lshl_add_u64 v[96:97], v[96:97], 0, v[100:101]
	global_load_dwordx4 v[16:19], v[96:97], off
	v_lshl_add_u64 v[96:97], v[96:97], 0, v[100:101]
	global_load_dwordx4 v[20:23], v[96:97], off
	v_lshl_add_u64 v[96:97], v[96:97], 0, v[100:101]
	global_load_dwordx4 v[24:27], v[96:97], off
	v_lshl_add_u64 v[96:97], v[96:97], 0, v[100:101]
	global_load_dwordx4 v[28:31], v[96:97], off
.Lw0_ld_done:
	s_or_b64 exec, exec, s[6:7]
	s_cmp_eq_u64 s[86:87], 0
	s_cbranch_scc1 .LBB0_124
	v_lshl_add_u64 v[102:103], v[98:99], 2, s[86:87]
	global_load_dword v104, v[102:103], off
	global_load_dword v105, v[102:103], off offset:32
	global_load_dword v106, v[102:103], off offset:64
	global_load_dword v107, v[102:103], off offset:96
	global_load_dword v108, v[102:103], off offset:128
	global_load_dword v109, v[102:103], off offset:160
	global_load_dword v110, v[102:103], off offset:192
	global_load_dword v111, v[102:103], off offset:224
	v_mov_b32_e32 v114, 1

; template <bool NT = false>
; __device__ __forceinline__ void wconv_load(const WItem& t, f32x4 (&v)[8]) {
;     const int tid = threadIdx.x;
; #pragma unroll
;     for (int i = 0; i < 8; ++i) {
;         const int idx = tid + i * 512, kk = idx >> 6, c4 = (idx & 63) * 4;
;         v[i] = (f32x4){0.f, 0.f, 0.f, 0.f};
;         if (t.n0 + c4 + 3 < t.ncols) { const f32x4* sp = (const f32x4*)(t.src + (size_t)(t.k0 + kk) * t.ld + t.n0 + c4); v[i] = NT ? __builtin_nontemporal_load(sp) : *sp; }
;         if (t.gk) v[i] = v[i] * t.gk[t.k0 + kk];
;     }
; }
; __global__ void __launch_bounds__(512, 2) mk_fwd(Args a) {
;     ...
;               if (nit > 0) wconv_load<true>(ffn_witem(MK_WIDX(0), a.in[16], a.in[17], a.in[18], ws, a.in[15]), v);
.LBB0_753:
	v_or3_b32 v0, v38, s12, 3
	v_cmp_gt_i32_e64 s[4:5], s18, v0
	v_add_u32_e32 v76, s16, v168
	v_lshlrev_b32_e32 v90, 2, v38
	v_mov_b32_e32 v91, 0
	v_mov_b32_e32 v169, 0
	v_mov_b32_e32 v0, 0
	v_mov_b32_e32 v1, 0
	v_mov_b32_e32 v2, 0
	v_mov_b32_e32 v3, 0
	v_mov_b32_e32 v4, 0
	v_mov_b32_e32 v5, 0
	v_mov_b32_e32 v6, 0
	v_mov_b32_e32 v7, 0
	v_mov_b32_e32 v8, 0
	v_mov_b32_e32 v9, 0
	v_mov_b32_e32 v10, 0
	v_mov_b32_e32 v11, 0
	v_mov_b32_e32 v12, 0
	v_mov_b32_e32 v13, 0
	v_mov_b32_e32 v14, 0
	v_mov_b32_e32 v15, 0
	v_mov_b32_e32 v16, 0
	v_mov_b32_e32 v17, 0
	v_mov_b32_e32 v18, 0
	v_mov_b32_e32 v19, 0
	v_mov_b32_e32 v20, 0
	v_mov_b32_e32 v21, 0
	v_mov_b32_e32 v22, 0
	v_mov_b32_e32 v23, 0
	v_mov_b32_e32 v24, 0
	v_mov_b32_e32 v25, 0
	v_mov_b32_e32 v26, 0
	v_mov_b32_e32 v27, 0
	v_mov_b32_e32 v28, 0
	v_mov_b32_e32 v29, 0
	v_mov_b32_e32 v30, 0
	v_mov_b32_e32 v31, 0
	v_mov_b32_e32 v92, 0
	v_lshlrev_b32_e64 v88, 5, s18
	v_mov_b32_e32 v89, 0
	v_mov_b32_e32 v77, 0
	s_and_saveexec_b64 s[6:7], s[4:5]
	s_cbranch_execz .Lw4p_ld_done
	v_mad_i64_i32 v[74:75], s[8:9], v76, s18, 0
	v_lshl_add_u64 v[74:75], v[74:75], 2, s[14:15]
	s_ashr_i32 s13, s12, 31
	v_lshl_add_u64 v[74:75], s[12:13], 2, v[74:75]
	v_lshl_add_u64 v[74:75], v[74:75], 0, v[90:91]
	global_load_dwordx4 v[0:3], v[74:75], off nt
	v_lshl_add_u64 v[74:75], v[74:75], 0, v[88:89]
	global_load_dwordx4 v[4:7], v[74:75], off nt
	v_lshl_add_u64 v[74:75], v[74:75], 0, v[88:89]
	global_load_dwordx4 v[8:11], v[74:75], off nt
	v_lshl_add_u64 v[74:75], v[74:75], 0, v[88:89]
	global_load_dwordx4 v[12:15], v[74:75], off nt
	v_lshl_add_u64 v[74:75], v[74:75], 0, v[88:89]
	global_load_dwordx4 v[16:19], v[74:75], off nt
	v_lshl_add_u64 v[74:75], v[74:75], 0, v[88:89]
	global_load_dwordx4 v[20:23], v[74:75], off nt
	v_lshl_add_u64 v[74:75], v[74:75], 0, v[88:89]
	global_load_dwordx4 v[24:27], v[74:75], off nt
	v_lshl_add_u64 v[74:75], v[74:75], 0, v[88:89]
	global_load_dwordx4 v[28:31], v[74:75], off nt

; #define LAS __attribute__((address_space(3)))
; template <bool NT = false>
; __device__ __forceinline__ void wconv_load(const WItem& t, f32x4 (&v)[8]) {
;     ...
;         if (t.gk) v[i] = v[i] * t.gk[t.k0 + kk];
;     }
; }
; __device__ __forceinline__ void wconv_commit(const f32x4 (&v)[8], LAS float* tile) {
;     const int tid = threadIdx.x;
; #pragma unroll
;     for (int i = 0; i < 8; ++i) {
;         const int idx = tid + i * 512, kk = idx >> 6, c4 = (idx & 63) * 4;
;         tile[kk * 257 + c4 + 0] = v[i][0]; tile[kk * 257 + c4 + 1] = v[i][1]; tile[kk * 257 + c4 + 2] = v[i][2]; tile[kk * 257 + c4 + 3] = v[i][3];
.LBB0_790:
	s_waitcnt vmcnt(0)
	v_cmp_ne_u32_e32 vcc, 0, v92
	s_cbranch_vccz .Lw4_nomul
	v_mul_f32_e32 v0, v80, v0
	v_mul_f32_e32 v1, v80, v1
	v_mul_f32_e32 v2, v80, v2
	v_mul_f32_e32 v3, v80, v3
	v_mul_f32_e32 v4, v81, v4
	v_mul_f32_e32 v5, v81, v5
	v_mul_f32_e32 v6, v81, v6
	v_mul_f32_e32 v7, v81, v7
	v_mul_f32_e32 v8, v82, v8
	v_mul_f32_e32 v9, v82, v9
	v_mul_f32_e32 v10, v82, v10
	v_mul_f32_e32 v11, v82, v11
	v_mul_f32_e32 v12, v83, v12
	v_mul_f32_e32 v13, v83, v13
	v_mul_f32_e32 v14, v83, v14
	v_mul_f32_e32 v15, v83, v15
	v_mul_f32_e32 v16, v84, v16
	v_mul_f32_e32 v17, v84, v17
	v_mul_f32_e32 v18, v84, v18
	v_mul_f32_e32 v19, v84, v19
	v_mul_f32_e32 v20, v85, v20
	v_mul_f32_e32 v21, v85, v21
	v_mul_f32_e32 v22, v85, v22
	v_mul_f32_e32 v23, v85, v23
	v_mul_f32_e32 v24, v86, v24
	v_mul_f32_e32 v25, v86, v25
	v_mul_f32_e32 v26, v86, v26
	v_mul_f32_e32 v27, v86, v27
	v_mul_f32_e32 v28, v87, v28
	v_mul_f32_e32 v29, v87, v29
	v_mul_f32_e32 v30, v87, v30
	v_mul_f32_e32 v31, v87, v31
	v_mov_b32_e32 v92, 0

; template <bool NT = false>
; __device__ __forceinline__ void wconv_load(const WItem& t, f32x4 (&v)[8]) {
;     const int tid = threadIdx.x;
; #pragma unroll
;     for (int i = 0; i < 8; ++i) {
;         const int idx = tid + i * 512, kk = idx >> 6, c4 = (idx & 63) * 4;
;         v[i] = (f32x4){0.f, 0.f, 0.f, 0.f};
;         if (t.n0 + c4 + 3 < t.ncols) { const f32x4* sp = (const f32x4*)(t.src + (size_t)(t.k0 + kk) * t.ld + t.n0 + c4); v[i] = NT ? __builtin_nontemporal_load(sp) : *sp; }
;         if (t.gk) v[i] = v[i] * t.gk[t.k0 + kk];
;     }
; }
; __global__ void __launch_bounds__(512, 2) mk_fwd(Args a) {
;     ...
;               for (int j = 0; j < nit; ++j) { wconv_commit(v, tile); __syncthreads(); if (j + 1 < nit) wconv_load<true>(ffn_witem(MK_WIDX(j + 1), a.in[16], a.in[17], a.in[18], ws, a.in[15]), v);
.LBB0_799:
	v_or_b32_e32 v0, s14, v57
	v_cmp_gt_i32_e64 s[4:5], s35, v0
	v_add_u32_e32 v76, s18, v168
	v_mov_b32_e32 v37, v35
	v_mov_b32_e32 v0, 0
	v_mov_b32_e32 v1, 0
	v_mov_b32_e32 v2, 0
	v_mov_b32_e32 v3, 0
	v_mov_b32_e32 v4, 0
	v_mov_b32_e32 v5, 0
	v_mov_b32_e32 v6, 0
	v_mov_b32_e32 v7, 0
	v_mov_b32_e32 v8, 0
	v_mov_b32_e32 v9, 0
	v_mov_b32_e32 v10, 0
	v_mov_b32_e32 v11, 0
	v_mov_b32_e32 v12, 0
	v_mov_b32_e32 v13, 0
	v_mov_b32_e32 v14, 0
	v_mov_b32_e32 v15, 0
	v_mov_b32_e32 v16, 0
	v_mov_b32_e32 v17, 0
	v_mov_b32_e32 v18, 0
	v_mov_b32_e32 v19, 0
	v_mov_b32_e32 v20, 0
	v_mov_b32_e32 v21, 0
	v_mov_b32_e32 v22, 0
	v_mov_b32_e32 v23, 0
	v_mov_b32_e32 v24, 0
	v_mov_b32_e32 v25, 0
	v_mov_b32_e32 v26, 0
	v_mov_b32_e32 v27, 0
	v_mov_b32_e32 v28, 0
	v_mov_b32_e32 v29, 0
	v_mov_b32_e32 v30, 0
	v_mov_b32_e32 v31, 0
	v_mov_b32_e32 v92, 0
	v_lshlrev_b32_e64 v88, 5, s35
	v_mov_b32_e32 v89, 0
	v_mov_b32_e32 v77, 0
	s_and_saveexec_b64 s[6:7], s[4:5]
	s_cbranch_execz .Lw4_ld_done
	v_mad_i64_i32 v[74:75], s[8:9], v76, s35, 0
	v_lshl_add_u64 v[74:75], v[74:75], 2, s[16:17]
	s_ashr_i32 s15, s14, 31
	v_lshl_add_u64 v[74:75], s[14:15], 2, v[74:75]
	v_lshl_add_u64 v[74:75], v[74:75], 0, v[36:37]
	global_load_dwordx4 v[0:3], v[74:75], off nt
	v_lshl_add_u64 v[74:75], v[74:75], 0, v[88:89]
	global_load_dwordx4 v[4:7], v[74:75], off nt
	v_lshl_add_u64 v[74:75], v[74:75], 0, v[88:89]
	global_load_dwordx4 v[8:11], v[74:75], off nt
	v_lshl_add_u64 v[74:75], v[74:75], 0, v[88:89]
	global_load_dwordx4 v[12:15], v[74:75], off nt
	v_lshl_add_u64 v[74:75], v[74:75], 0, v[88:89]
	global_load_dwordx4 v[16:19], v[74:75], off nt
	v_lshl_add_u64 v[74:75], v[74:75], 0, v[88:89]
	global_load_dwordx4 v[20:23], v[74:75], off nt
	v_lshl_add_u64 v[74:75], v[74:75], 0, v[88:89]
	global_load_dwordx4 v[24:27], v[74:75], off nt
	v_lshl_add_u64 v[74:75], v[74:75], 0, v[88:89]
	global_load_dwordx4 v[28:31], v[74:75], off nt
.Lw4_ld_done:
	s_or_b64 exec, exec, s[6:7]
	s_cmp_eq_u64 s[12:13], 0
	s_cbranch_scc1 .LBB0_831
	v_lshl_add_u64 v[78:79], v[76:77], 2, s[12:13]
	global_load_dword v80, v[78:79], off
	global_load_dword v81, v[78:79], off offset:32
	global_load_dword v82, v[78:79], off offset:64
	global_load_dword v83, v[78:79], off offset:96
	global_load_dword v84, v[78:79], off offset:128
	global_load_dword v85, v[78:79], off offset:160
	global_load_dword v86, v[78:79], off offset:192
	global_load_dword v87, v[78:79], off offset:224
	v_mov_b32_e32 v92, 1
